# attention loop: incremental K/krope row pointers (3 VALU per tile instead of 27 address ops), 8 LDS temp quads
# speedup vs baseline: 1.0603x; 1.0078x over previous
.Lattn3_setup:
	v_mov_b32_e32 v234, 0x10000
	v_mov_b32_e32 v235, 0x1000
	v_add_u32_e32 v32, s24, v147
	v_ashrrev_i32_e32 v33, 31, v32
	v_lshlrev_b64 v[34:35], 10, v[32:33]
	v_lshlrev_b64 v[32:33], 6, v[32:33]
	v_lshl_add_u64 v[32:33], v[118:119], 0, v[32:33]
	v_lshl_add_u64 v[34:35], v[120:121], 0, v[34:35]
	v_lshl_add_u64 v[32:33], v[32:33], 0, s[14:15]
	v_cndmask_b32_e32 v33, v33, v35, vcc
	v_cndmask_b32_e32 v32, v32, v34, vcc
	v_mov_b32_e32 v244, v32
	v_mov_b32_e32 v245, v33
	v_cndmask_b32_e32 v228, v235, v234, vcc
	v_mov_b32_e32 v229, 0
	v_add_u32_e32 v32, s24, v146
	v_ashrrev_i32_e32 v33, 31, v32
	v_lshlrev_b64 v[34:35], 10, v[32:33]
	v_lshlrev_b64 v[32:33], 6, v[32:33]
	v_lshl_add_u64 v[32:33], v[122:123], 0, v[32:33]
	v_lshl_add_u64 v[34:35], v[124:125], 0, v[34:35]
	v_lshl_add_u64 v[32:33], v[32:33], 0, s[14:15]
	v_cndmask_b32_e64 v33, v33, v35, s[6:7]
	v_cndmask_b32_e64 v32, v32, v34, s[6:7]
	v_mov_b32_e32 v246, v32
	v_mov_b32_e32 v247, v33
	v_cndmask_b32_e64 v230, v235, v234, s[6:7]
	v_mov_b32_e32 v231, 0
	v_add_u32_e32 v32, s24, v145
	v_ashrrev_i32_e32 v33, 31, v32
	v_lshlrev_b64 v[34:35], 10, v[32:33]
	v_lshlrev_b64 v[32:33], 6, v[32:33]
	v_lshl_add_u64 v[32:33], v[126:127], 0, v[32:33]
	v_lshl_add_u64 v[34:35], v[130:131], 0, v[34:35]
	v_lshl_add_u64 v[32:33], v[32:33], 0, s[14:15]
	v_cndmask_b32_e64 v33, v33, v35, s[4:5]
	v_cndmask_b32_e64 v32, v32, v34, s[4:5]
	v_mov_b32_e32 v248, v32
	v_mov_b32_e32 v249, v33
	v_cndmask_b32_e64 v232, v235, v234, s[4:5]
	v_mov_b32_e32 v233, 0
.LBB0_1674:
	s_and_b32 s9, s2, 1
	global_load_dwordx4 v[88:91], v[244:245], off
	global_load_dwordx4 v[92:95], v[246:247], off
	global_load_dwordx4 v[96:99], v[248:249], off
	s_mul_i32 s12, s9, 0x3400
	global_load_dwordx4 v[104:107], v[134:135], off
	global_load_dwordx4 v[100:103], v[132:133], off
	v_lshl_add_u64 v[244:245], v[244:245], 0, v[228:229]
	v_lshl_add_u64 v[246:247], v[246:247], 0, v[230:231]
	v_lshl_add_u64 v[248:249], v[248:249], 0, v[232:233]
	v_or_b32_e32 v32, s12, v143
	v_mov_b32_e32 v153, v115
	v_add_u32_e32 v115, v32, v117
	ds_read_b128 v[164:167], v115
	ds_read_b128 v[168:171], v115 offset:32
	ds_read_b128 v[172:175], v115 offset:64
	ds_read_b128 v[180:183], v115 offset:96
	ds_read_b128 v[184:187], v115 offset:128
	ds_read_b128 v[188:191], v115 offset:160
	ds_read_b128 v[192:195], v115 offset:6656
	ds_read_b128 v[196:199], v115 offset:6688
	v_mov_b32_e32 v152, v148
	s_mul_i32 s12, s9, 0x2200
	s_xor_b32 s9, s9, 1
	s_add_i32 s2, s2, 1
	s_add_i32 s24, s24, 64
	v_add_u32_e32 v200, s12, v144
	v_lshl_add_u64 v[132:133], v[132:133], 0, s[68:69]
	v_lshl_add_u64 v[134:135], v[134:135], 0, s[68:69]
	v_add_u32_e32 v200, 0x6800, v200
	v_add_u32_e32 v201, 0x1000, v200
	s_waitcnt lgkmcnt(7)
	v_mfma_f32_32x32x16_bf16 v[48:63], v[164:167], v[64:67], 0
	ds_read_b128 v[164:167], v115 offset:6720
	s_waitcnt lgkmcnt(7)
	v_mfma_f32_32x32x16_bf16 v[48:63], v[168:171], v[68:71], v[48:63]
	ds_read_b128 v[168:171], v115 offset:6752
	s_waitcnt lgkmcnt(7)
	v_mfma_f32_32x32x16_bf16 v[48:63], v[172:175], v[76:79], v[48:63]
	ds_read_b128 v[172:175], v115 offset:6784
	s_waitcnt lgkmcnt(7)
	v_mfma_f32_32x32x16_bf16 v[48:63], v[180:183], v[72:75], v[48:63]
	ds_read_b128 v[180:183], v115 offset:6816
	s_waitcnt lgkmcnt(7)
	v_mfma_f32_32x32x16_bf16 v[48:63], v[184:187], v[80:83], v[48:63]
	s_waitcnt lgkmcnt(6)
	v_mfma_f32_32x32x16_bf16 v[48:63], v[188:191], v[84:87], v[48:63]
	s_waitcnt lgkmcnt(5)
	v_mfma_f32_32x32x16_bf16 v[32:47], v[192:195], v[64:67], 0
	s_waitcnt lgkmcnt(4)
	v_mfma_f32_32x32x16_bf16 v[32:47], v[196:199], v[68:71], v[32:47]
	s_waitcnt lgkmcnt(3)
	v_mfma_f32_32x32x16_bf16 v[32:47], v[164:167], v[76:79], v[32:47]
	s_waitcnt lgkmcnt(2)
	v_mfma_f32_32x32x16_bf16 v[32:47], v[168:171], v[72:75], v[32:47]
	s_waitcnt lgkmcnt(1)
	v_mfma_f32_32x32x16_bf16 v[32:47], v[172:175], v[80:83], v[32:47]
	s_waitcnt lgkmcnt(0)
	v_mfma_f32_32x32x16_bf16 v[32:47], v[180:183], v[84:87], v[32:47]
	ds_read2_b64 v[164:167], v200 offset1:2
	ds_read2_b64 v[168:171], v201 offset0:32 offset1:34
	ds_read2_b64 v[172:175], v201 offset0:36 offset1:38
	ds_read2_b64 v[180:183], v200 offset0:4 offset1:6
	ds_read2_b64 v[184:187], v200 offset0:8 offset1:10
	ds_read2_b64 v[188:191], v201 offset0:40 offset1:42
	ds_read2_b64 v[192:195], v200 offset0:12 offset1:14
	ds_read2_b64 v[196:199], v201 offset0:44 offset1:46
	v_max_f32_e32 v115, v49, v49
	v_max_f32_e32 v148, v48, v48
	v_max_f32_e32 v115, v148, v115
	v_max3_f32 v115, v115, v50, v51
	v_max3_f32 v115, v115, v52, v53
	v_max3_f32 v115, v115, v54, v55
	v_max3_f32 v115, v115, v56, v57
	v_max3_f32 v115, v115, v58, v59
	v_max3_f32 v115, v115, v60, v61
	v_max3_f32 v115, v115, v62, v63
	s_nop 2
	v_max3_f32 v115, v115, v32, v33
	v_max3_f32 v115, v115, v34, v35
	v_max3_f32 v115, v115, v36, v37
	v_max3_f32 v115, v115, v38, v39
	v_max3_f32 v115, v115, v40, v41
	v_max3_f32 v115, v115, v42, v43
	v_max3_f32 v115, v115, v44, v45
	v_max3_f32 v115, v115, v46, v47
	ds_bpermute_b32 v148, v111, v115
	s_waitcnt lgkmcnt(0)
	v_max3_f32 v148, v152, v115, v148
	v_sub_f32_e32 v48, v48, v148
	v_exp_f32_e32 v48, v48
	v_sub_f32_e32 v49, v49, v148
	v_exp_f32_e32 v49, v49
	v_sub_f32_e32 v50, v50, v148
	v_exp_f32_e32 v50, v50
	v_sub_f32_e32 v51, v51, v148
	v_sub_f32_e32 v115, v152, v148
	v_exp_f32_e32 v51, v51
	v_sub_f32_e32 v52, v52, v148
	v_exp_f32_e32 v150, v115
	v_add_f32_e32 v115, 0, v48
	v_exp_f32_e32 v52, v52
	v_sub_f32_e32 v53, v53, v148
	v_sub_f32_e32 v32, v32, v148
	v_add_f32_e32 v115, v49, v115
	v_exp_f32_e32 v53, v53
	v_sub_f32_e32 v54, v54, v148
	v_exp_f32_e32 v149, v32
	v_sub_f32_e32 v32, v33, v148
	v_add_f32_e32 v115, v50, v115
	v_exp_f32_e32 v54, v54
	v_sub_f32_e32 v55, v55, v148
	v_exp_f32_e32 v151, v32
	v_sub_f32_e32 v32, v34, v148
	v_add_f32_e32 v115, v51, v115
	v_exp_f32_e32 v55, v55
	v_sub_f32_e32 v56, v56, v148
	v_exp_f32_e32 v152, v32
	v_sub_f32_e32 v32, v35, v148
	v_add_f32_e32 v115, v52, v115
	v_exp_f32_e32 v56, v56
	v_sub_f32_e32 v57, v57, v148
	v_exp_f32_e32 v154, v32
	v_sub_f32_e32 v32, v36, v148
	v_add_f32_e32 v115, v53, v115
	v_exp_f32_e32 v57, v57
	v_sub_f32_e32 v58, v58, v148
	v_exp_f32_e32 v155, v32
	v_sub_f32_e32 v32, v37, v148
	v_add_f32_e32 v115, v54, v115
	v_exp_f32_e32 v58, v58
	v_sub_f32_e32 v59, v59, v148
	v_exp_f32_e32 v156, v32
	v_sub_f32_e32 v32, v38, v148
	v_add_f32_e32 v115, v55, v115
	v_exp_f32_e32 v59, v59
	v_sub_f32_e32 v60, v60, v148
	v_exp_f32_e32 v157, v32
	v_sub_f32_e32 v32, v39, v148
	v_add_f32_e32 v115, v56, v115
	v_exp_f32_e32 v60, v60
	v_sub_f32_e32 v61, v61, v148
	v_exp_f32_e32 v158, v32
	v_sub_f32_e32 v32, v40, v148
	v_add_f32_e32 v115, v57, v115
	v_exp_f32_e32 v61, v61
	v_sub_f32_e32 v62, v62, v148
	v_exp_f32_e32 v159, v32
	v_sub_f32_e32 v32, v41, v148
	v_add_f32_e32 v115, v58, v115
	v_exp_f32_e32 v62, v62
	v_sub_f32_e32 v63, v63, v148
	v_exp_f32_e32 v160, v32
	v_sub_f32_e32 v32, v42, v148
	v_add_f32_e32 v115, v59, v115
	v_exp_f32_e32 v63, v63
	v_exp_f32_e32 v161, v32
	v_sub_f32_e32 v32, v43, v148
	v_add_f32_e32 v115, v60, v115
	v_exp_f32_e32 v162, v32
	v_sub_f32_e32 v32, v44, v148
	v_add_f32_e32 v115, v61, v115
	v_exp_f32_e32 v44, v32
	v_sub_f32_e32 v32, v45, v148
	v_add_f32_e32 v115, v62, v115
	v_exp_f32_e32 v45, v32
	v_sub_f32_e32 v32, v46, v148
	v_add_f32_e32 v115, v63, v115
	v_exp_f32_e32 v46, v32
	v_sub_f32_e32 v32, v47, v148
	v_exp_f32_e32 v47, v32
	v_add_f32_e32 v32, v149, v115
	v_add_f32_e32 v32, v151, v32
	v_add_f32_e32 v32, v152, v32
	v_add_f32_e32 v32, v154, v32
	v_add_f32_e32 v32, v155, v32
	v_add_f32_e32 v32, v156, v32
	v_add_f32_e32 v32, v157, v32
	v_add_f32_e32 v32, v158, v32
	v_add_f32_e32 v32, v159, v32
	v_add_f32_e32 v32, v160, v32
	v_add_f32_e32 v32, v161, v32
	v_add_f32_e32 v32, v162, v32
	v_add_f32_e32 v32, v44, v32
	v_add_f32_e32 v32, v45, v32
	v_add_f32_e32 v32, v46, v32
	v_add_f32_e32 v115, v47, v32
	v_cvt_pk_bf16_f32 v32, v48, v49
	v_pk_mul_f32 v[30:31], v[30:31], v[150:151] op_sel_hi:[1,0]
	v_pk_mul_f32 v[28:29], v[28:29], v[150:151] op_sel_hi:[1,0]
	v_pk_mul_f32 v[26:27], v[26:27], v[150:151] op_sel_hi:[1,0]
	v_pk_mul_f32 v[24:25], v[24:25], v[150:151] op_sel_hi:[1,0]
	v_pk_mul_f32 v[22:23], v[22:23], v[150:151] op_sel_hi:[1,0]
	v_pk_mul_f32 v[20:21], v[20:21], v[150:151] op_sel_hi:[1,0]
	v_pk_mul_f32 v[18:19], v[18:19], v[150:151] op_sel_hi:[1,0]
	v_pk_mul_f32 v[16:17], v[16:17], v[150:151] op_sel_hi:[1,0]
	v_cvt_pk_bf16_f32 v33, v50, v51
	v_cvt_pk_bf16_f32 v34, v52, v53
	v_cvt_pk_bf16_f32 v35, v54, v55
	v_pk_mul_f32 v[14:15], v[14:15], v[150:151] op_sel_hi:[1,0]
	v_mul_f32_e64 v12, v12, v150
	v_mul_f32_e64 v13, v13, v150
	v_mul_f32_e64 v10, v10, v150
	v_mul_f32_e64 v11, v11, v150
	v_pk_mul_f32 v[8:9], v[8:9], v[150:151] op_sel_hi:[1,0]
	v_pk_mul_f32 v[6:7], v[6:7], v[150:151] op_sel_hi:[1,0]
	v_pk_mul_f32 v[4:5], v[4:5], v[150:151] op_sel_hi:[1,0]
	v_pk_mul_f32 v[2:3], v[2:3], v[150:151] op_sel_hi:[1,0]
	v_pk_mul_f32 v[0:1], v[0:1], v[150:151] op_sel_hi:[1,0]
	s_mul_i32 s12, s9, 0x3400
	s_mulk_i32 s9, 0xee00
	s_waitcnt lgkmcnt(0)
	v_mfma_f32_32x32x16_bf16 v[16:31], v[164:167], v[32:35], v[16:31]
	v_mfma_f32_32x32x16_bf16 v[0:15], v[168:171], v[32:35], v[0:15]
	v_cvt_pk_bf16_f32 v32, v56, v57
	v_cvt_pk_bf16_f32 v33, v58, v59
	v_cvt_pk_bf16_f32 v34, v60, v61
	v_cvt_pk_bf16_f32 v35, v62, v63
	v_fmac_f32_e32 v115, v153, v150
	s_nop 0
	v_mfma_f32_32x32x16_bf16 v[0:15], v[172:175], v[32:35], v[0:15]
	v_mfma_f32_32x32x16_bf16 v[16:31], v[180:183], v[32:35], v[16:31]
	v_cvt_pk_bf16_f32 v32, v149, v151
	v_cvt_pk_bf16_f32 v33, v152, v154
	v_cvt_pk_bf16_f32 v34, v155, v156
	v_cvt_pk_bf16_f32 v35, v157, v158
	s_nop 1
	v_mfma_f32_32x32x16_bf16 v[16:31], v[184:187], v[32:35], v[16:31]
	v_mfma_f32_32x32x16_bf16 v[0:15], v[188:191], v[32:35], v[0:15]
	v_cvt_pk_bf16_f32 v32, v159, v160
	v_cvt_pk_bf16_f32 v33, v161, v162
	v_cvt_pk_bf16_f32 v34, v44, v45
	v_cvt_pk_bf16_f32 v35, v46, v47
	s_nop 1
	v_mfma_f32_32x32x16_bf16 v[16:31], v[192:195], v[32:35], v[16:31]
	v_mfma_f32_32x32x16_bf16 v[0:15], v[196:199], v[32:35], v[0:15]
	v_lshlrev_b32_e32 v32, 1, v137
	v_lshlrev_b32_e32 v33, 1, v114
	v_add3_u32 v32, s12, v32, v33
	s_waitcnt vmcnt(4)
	ds_write_b128 v32, v[88:91]
	v_lshlrev_b32_e32 v32, 1, v138
	v_lshlrev_b32_e32 v33, 1, v116
	v_add3_u32 v32, s12, v32, v33
	s_waitcnt vmcnt(3)
	ds_write_b128 v32, v[92:95]
	v_lshlrev_b32_e32 v32, 1, v139
	v_add3_u32 v32, s12, v32, v140
	s_add_i32 s12, s12, s9
	s_waitcnt vmcnt(2)
	ds_write_b128 v32, v[96:99]
	v_lshl_add_u32 v32, v141, 1, s12
	v_add3_u32 v32, v32, v128, s42
	s_waitcnt vmcnt(1)
	ds_write2_b64 v32, v[104:105], v[106:107] offset1:1
	v_lshl_add_u32 v32, v142, 1, s12
	v_add3_u32 v32, v32, v128, s42
	s_cmp_lg_u32 s8, s2
	s_waitcnt vmcnt(0)
	ds_write2_b64 v32, v[100:101], v[102:103] offset1:1
	s_waitcnt lgkmcnt(0)
	s_barrier
	s_cbranch_scc1 .LBB0_1674
	s_and_b32 s2, s8, 1
	s_mul_i32 s4, s2, 0x3400
	v_or_b32_e32 v32, s4, v143
	v_add_u32_e32 v88, v32, v117
	ds_read_b128 v[32:35], v88
	ds_read_b128 v[36:39], v88 offset:32
	s_mulk_i32 s2, 0x2200
	s_waitcnt lgkmcnt(1)
	v_mfma_f32_32x32x16_bf16 v[48:63], v[32:35], v[64:67], 0
	ds_read_b128 v[32:35], v88 offset:64
	s_waitcnt lgkmcnt(1)
	v_mfma_f32_32x32x16_bf16 v[48:63], v[36:39], v[68:71], v[48:63]
	s_waitcnt lgkmcnt(0)
	v_mfma_f32_32x32x16_bf16 v[48:63], v[32:35], v[76:79], v[48:63]
	ds_read_b128 v[32:35], v88 offset:96
	s_waitcnt lgkmcnt(0)
	v_mfma_f32_32x32x16_bf16 v[48:63], v[32:35], v[72:75], v[48:63]
	ds_read_b128 v[32:35], v88 offset:128
	s_waitcnt lgkmcnt(0)
	v_mfma_f32_32x32x16_bf16 v[48:63], v[32:35], v[80:83], v[48:63]
	ds_read_b128 v[32:35], v88 offset:160
	s_waitcnt lgkmcnt(0)
	v_mfma_f32_32x32x16_bf16 v[48:63], v[32:35], v[84:87], v[48:63]
	ds_read_b128 v[32:35], v88 offset:6656
	s_waitcnt lgkmcnt(0)
	v_mfma_f32_32x32x16_bf16 v[32:47], v[32:35], v[64:67], 0
	ds_read_b128 v[64:67], v88 offset:6688
	s_waitcnt lgkmcnt(0)
	v_mfma_f32_32x32x16_bf16 v[32:47], v[64:67], v[68:71], v[32:47]
	ds_read_b128 v[64:67], v88 offset:6720
	s_waitcnt lgkmcnt(0)
	v_mfma_f32_32x32x16_bf16 v[32:47], v[64:67], v[76:79], v[32:47]
	ds_read_b128 v[64:67], v88 offset:6752
	s_waitcnt lgkmcnt(0)
	v_mfma_f32_32x32x16_bf16 v[32:47], v[64:67], v[72:75], v[32:47]
	ds_read_b128 v[64:67], v88 offset:6784
	s_waitcnt lgkmcnt(0)
	v_mfma_f32_32x32x16_bf16 v[32:47], v[64:67], v[80:83], v[32:47]
	ds_read_b128 v[64:67], v88 offset:6816
	s_waitcnt lgkmcnt(0)
	v_mfma_f32_32x32x16_bf16 v[32:47], v[64:67], v[84:87], v[32:47]
	v_max_f32_e32 v64, v49, v49
	v_max_f32_e32 v65, v48, v48
	v_max_f32_e32 v64, v65, v64
	v_max3_f32 v64, v64, v50, v51
	v_max3_f32 v64, v64, v52, v53
	v_max3_f32 v64, v64, v54, v55
	v_max3_f32 v64, v64, v56, v57
	v_max3_f32 v64, v64, v58, v59
	v_max3_f32 v64, v64, v60, v61
	v_max3_f32 v64, v64, v62, v63
	s_nop 1
	v_max3_f32 v64, v64, v32, v33
	v_max3_f32 v64, v64, v34, v35
	v_max3_f32 v64, v64, v36, v37
	v_max3_f32 v64, v64, v38, v39
	v_max3_f32 v64, v64, v40, v41
	v_max3_f32 v64, v64, v42, v43
	v_max3_f32 v64, v64, v44, v45
	v_max3_f32 v64, v64, v46, v47
	ds_bpermute_b32 v65, v111, v64
	s_waitcnt lgkmcnt(0)
	v_max3_f32 v65, v148, v64, v65
	v_sub_f32_e32 v48, v48, v65
	v_exp_f32_e32 v48, v48
	v_sub_f32_e32 v49, v49, v65
	v_exp_f32_e32 v49, v49
	v_sub_f32_e32 v50, v50, v65
	v_exp_f32_e32 v50, v50
	v_sub_f32_e32 v51, v51, v65
	v_exp_f32_e32 v51, v51
	v_sub_f32_e32 v52, v52, v65
	v_add_f32_e32 v66, 0, v48
	v_exp_f32_e32 v52, v52
	v_sub_f32_e32 v53, v53, v65
	v_sub_f32_e32 v32, v32, v65
	v_add_f32_e32 v66, v49, v66
	v_exp_f32_e32 v53, v53
	v_sub_f32_e32 v54, v54, v65
	v_exp_f32_e32 v67, v32
	v_sub_f32_e32 v32, v33, v65
	v_add_f32_e32 v66, v50, v66
	v_exp_f32_e32 v54, v54
	v_sub_f32_e32 v55, v55, v65
	v_exp_f32_e32 v68, v32
	v_sub_f32_e32 v32, v34, v65
	v_add_f32_e32 v66, v51, v66
	v_exp_f32_e32 v55, v55
	v_sub_f32_e32 v56, v56, v65
	v_exp_f32_e32 v69, v32
	v_sub_f32_e32 v32, v35, v65
	v_add_f32_e32 v66, v52, v66
	v_exp_f32_e32 v56, v56
	v_sub_f32_e32 v57, v57, v65
	v_exp_f32_e32 v70, v32
	v_sub_f32_e32 v32, v36, v65
	v_add_f32_e32 v66, v53, v66
	v_exp_f32_e32 v57, v57
	v_sub_f32_e32 v58, v58, v65
	v_exp_f32_e32 v71, v32
	v_sub_f32_e32 v32, v37, v65
	v_add_f32_e32 v66, v54, v66
	v_exp_f32_e32 v58, v58
	v_sub_f32_e32 v59, v59, v65
	v_exp_f32_e32 v72, v32
	v_sub_f32_e32 v32, v38, v65
	v_add_f32_e32 v66, v55, v66
	v_exp_f32_e32 v59, v59
	v_sub_f32_e32 v60, v60, v65
	v_exp_f32_e32 v73, v32
	v_sub_f32_e32 v32, v39, v65
	v_add_f32_e32 v66, v56, v66
	v_exp_f32_e32 v60, v60
	v_sub_f32_e32 v61, v61, v65
	v_exp_f32_e32 v74, v32
	v_sub_f32_e32 v32, v40, v65
	v_add_f32_e32 v66, v57, v66
	v_exp_f32_e32 v61, v61
	v_sub_f32_e32 v62, v62, v65
	v_exp_f32_e32 v75, v32
	v_sub_f32_e32 v32, v41, v65
	v_add_f32_e32 v66, v58, v66
	v_exp_f32_e32 v62, v62
	v_sub_f32_e32 v63, v63, v65
	v_exp_f32_e32 v76, v32
	v_sub_f32_e32 v32, v42, v65
	v_add_f32_e32 v66, v59, v66
	v_exp_f32_e32 v63, v63
	v_exp_f32_e32 v77, v32
	v_sub_f32_e32 v32, v43, v65
	v_add_f32_e32 v66, v60, v66
	v_exp_f32_e32 v78, v32
	v_sub_f32_e32 v32, v44, v65
	v_add_f32_e32 v66, v61, v66
	v_exp_f32_e32 v44, v32
	v_sub_f32_e32 v32, v45, v65
	v_add_f32_e32 v66, v62, v66
	v_exp_f32_e32 v45, v32
	v_sub_f32_e32 v32, v46, v65
	v_add_f32_e32 v66, v63, v66
	v_exp_f32_e32 v46, v32
	v_sub_f32_e32 v32, v47, v65
	v_exp_f32_e32 v47, v32
	v_add_f32_e32 v32, v67, v66
	v_add_f32_e32 v32, v68, v32
	v_add_f32_e32 v32, v69, v32
	v_add_f32_e32 v32, v70, v32
	v_add_f32_e32 v32, v71, v32
	v_add_f32_e32 v32, v72, v32
	v_add_f32_e32 v32, v73, v32
	v_add_f32_e32 v32, v74, v32
	v_add_f32_e32 v32, v75, v32
	v_add_f32_e32 v32, v76, v32
	v_sub_f32_e32 v64, v148, v65
	v_add_f32_e32 v32, v77, v32
	v_exp_f32_e32 v64, v64
	v_add_f32_e32 v32, v78, v32
	v_add_f32_e32 v32, v44, v32
	v_add_f32_e32 v32, v45, v32
	v_add_f32_e32 v32, v46, v32
	v_lshlrev_b32_e32 v36, 1, v113
	v_pk_mul_f32 v[30:31], v[30:31], v[64:65] op_sel_hi:[1,0]
	v_pk_mul_f32 v[28:29], v[28:29], v[64:65] op_sel_hi:[1,0]
	v_pk_mul_f32 v[26:27], v[26:27], v[64:65] op_sel_hi:[1,0]
	v_pk_mul_f32 v[24:25], v[24:25], v[64:65] op_sel_hi:[1,0]
	v_pk_mul_f32 v[22:23], v[22:23], v[64:65] op_sel_hi:[1,0]
	v_pk_mul_f32 v[20:21], v[20:21], v[64:65] op_sel_hi:[1,0]
	v_pk_mul_f32 v[18:19], v[18:19], v[64:65] op_sel_hi:[1,0]
	v_pk_mul_f32 v[16:17], v[16:17], v[64:65] op_sel_hi:[1,0]
	v_pk_mul_f32 v[14:15], v[14:15], v[64:65] op_sel_hi:[1,0]
	v_pk_mul_f32 v[12:13], v[12:13], v[64:65] op_sel_hi:[1,0]
	v_pk_mul_f32 v[10:11], v[10:11], v[64:65] op_sel_hi:[1,0]
	v_pk_mul_f32 v[8:9], v[8:9], v[64:65] op_sel_hi:[1,0]
	v_pk_mul_f32 v[6:7], v[6:7], v[64:65] op_sel_hi:[1,0]
	v_pk_mul_f32 v[4:5], v[4:5], v[64:65] op_sel_hi:[1,0]
	v_pk_mul_f32 v[2:3], v[2:3], v[64:65] op_sel_hi:[1,0]
	v_pk_mul_f32 v[0:1], v[0:1], v[64:65] op_sel_hi:[1,0]
	v_add_f32_e32 v65, v47, v32
	v_cvt_pk_bf16_f32 v32, v48, v49
	v_add3_u32 v48, v136, s2, v36
	v_add_u32_e32 v49, 0x6800, v48
	ds_read2_b64 v[36:39], v49 offset1:2
	ds_read2_b64 v[40:43], v49 offset0:4 offset1:6
	v_cvt_pk_bf16_f32 v33, v50, v51
	v_cvt_pk_bf16_f32 v34, v52, v53
	v_cvt_pk_bf16_f32 v35, v54, v55
	v_add_u32_e32 v48, 0x7800, v48
	v_fmac_f32_e32 v65, v115, v64
	s_waitcnt lgkmcnt(1)
	v_mfma_f32_32x32x16_bf16 v[16:31], v[36:39], v[32:35], v[16:31]
	ds_read2_b64 v[36:39], v48 offset0:32 offset1:34
	v_mov_b32_e32 v113, v129
	s_mov_b32 s2, 0x15f20000
	s_waitcnt lgkmcnt(0)
	v_mfma_f32_32x32x16_bf16 v[0:15], v[36:39], v[32:35], v[0:15]
	ds_read2_b64 v[36:39], v48 offset0:36 offset1:38
	v_cvt_pk_bf16_f32 v32, v56, v57
	v_cvt_pk_bf16_f32 v33, v58, v59
	v_cvt_pk_bf16_f32 v34, v60, v61
	v_cvt_pk_bf16_f32 v35, v62, v63
	s_waitcnt lgkmcnt(0)
	s_nop 0
	v_mfma_f32_32x32x16_bf16 v[0:15], v[36:39], v[32:35], v[0:15]
	ds_read2_b64 v[36:39], v49 offset0:8 offset1:10
	v_mfma_f32_32x32x16_bf16 v[16:31], v[40:43], v[32:35], v[16:31]
	v_cvt_pk_bf16_f32 v32, v67, v68
	v_cvt_pk_bf16_f32 v33, v69, v70
	v_cvt_pk_bf16_f32 v34, v71, v72
	v_cvt_pk_bf16_f32 v35, v73, v74
	s_waitcnt lgkmcnt(0)
	s_nop 0
	v_mfma_f32_32x32x16_bf16 v[16:31], v[36:39], v[32:35], v[16:31]
	ds_read2_b64 v[36:39], v48 offset0:40 offset1:42
	s_waitcnt lgkmcnt(0)
	v_mfma_f32_32x32x16_bf16 v[0:15], v[36:39], v[32:35], v[0:15]
	ds_read2_b64 v[36:39], v49 offset0:12 offset1:14
	v_cvt_pk_bf16_f32 v32, v75, v76
	v_cvt_pk_bf16_f32 v33, v77, v78
	v_cvt_pk_bf16_f32 v34, v44, v45
	v_cvt_pk_bf16_f32 v35, v46, v47
	s_waitcnt lgkmcnt(0)
	s_nop 0
	v_mfma_f32_32x32x16_bf16 v[16:31], v[36:39], v[32:35], v[16:31]
	ds_read2_b64 v[36:39], v48 offset0:44 offset1:46
	s_waitcnt lgkmcnt(0)
	s_barrier
	v_mfma_f32_32x32x16_bf16 v[0:15], v[36:39], v[32:35], v[0:15]
	ds_bpermute_b32 v32, v111, v65
	v_mov_b32_e32 v111, v129
	s_waitcnt lgkmcnt(0)
	v_add_f32_e32 v32, v65, v32
	v_div_scale_f32 v33, s[4:5], v32, v32, 1.0
	v_rcp_f32_e32 v34, v33
	s_mov_b64 s[4:5], 0x15f20000
	v_fma_f32 v35, -v33, v34, 1.0
	v_fmac_f32_e32 v34, v35, v34
	v_div_scale_f32 v35, vcc, 1.0, v32, 1.0
	v_mul_f32_e32 v36, v35, v34
	v_fma_f32 v37, -v33, v36, v35
	v_fmac_f32_e32 v36, v37, v34
	v_fma_f32 v33, -v33, v36, v35
	v_div_fmas_f32 v33, v33, v34, v36
	v_lshlrev_b64 v[34:35], 10, v[108:109]
	v_lshl_add_u64 v[34:35], s[10:11], 0, v[34:35]
	v_div_fixup_f32 v32, v33, v32, 1.0
	v_lshl_add_u64 v[34:35], v[34:35], 0, v[112:113]
	v_lshl_add_u64 v[34:35], v[34:35], 0, v[110:111]
	v_pk_mul_f32 v[16:17], v[16:17], v[32:33] op_sel_hi:[1,0]
	v_pk_mul_f32 v[18:19], v[18:19], v[32:33] op_sel_hi:[1,0]
	v_cvt_pk_bf16_f32 v16, v16, v17
	v_cvt_pk_bf16_f32 v17, v18, v19
	v_add_co_u32_e32 v18, vcc, s2, v34
	v_pk_mul_f32 v[0:1], v[0:1], v[32:33] op_sel_hi:[1,0]
	v_pk_mul_f32 v[2:3], v[2:3], v[32:33] op_sel_hi:[1,0]
	v_lshl_add_u64 v[36:37], v[34:35], 0, s[4:5]
	v_addc_co_u32_e32 v19, vcc, 0, v35, vcc
	v_cvt_pk_bf16_f32 v0, v0, v1
	v_cvt_pk_bf16_f32 v1, v2, v3
	global_store_dwordx2 v[18:19], v[16:17], off
	v_pk_mul_f32 v[16:17], v[20:21], v[32:33] op_sel_hi:[1,0]
	v_pk_mul_f32 v[18:19], v[22:23], v[32:33] op_sel_hi:[1,0]
	global_store_dwordx2 v[36:37], v[0:1], off offset:64
	v_pk_mul_f32 v[0:1], v[4:5], v[32:33] op_sel_hi:[1,0]
	v_pk_mul_f32 v[2:3], v[6:7], v[32:33] op_sel_hi:[1,0]
	v_cvt_pk_bf16_f32 v16, v16, v17
	v_cvt_pk_bf16_f32 v17, v18, v19
	v_cvt_pk_bf16_f32 v0, v0, v1
	v_cvt_pk_bf16_f32 v1, v2, v3
	global_store_dwordx2 v[36:37], v[16:17], off offset:16
	v_pk_mul_f32 v[16:17], v[24:25], v[32:33] op_sel_hi:[1,0]
	v_pk_mul_f32 v[18:19], v[26:27], v[32:33] op_sel_hi:[1,0]
	global_store_dwordx2 v[36:37], v[0:1], off offset:80
	v_pk_mul_f32 v[0:1], v[8:9], v[32:33] op_sel_hi:[1,0]
	v_pk_mul_f32 v[2:3], v[10:11], v[32:33] op_sel_hi:[1,0]
	v_cvt_pk_bf16_f32 v16, v16, v17
	v_cvt_pk_bf16_f32 v17, v18, v19
	v_cvt_pk_bf16_f32 v0, v0, v1
	v_cvt_pk_bf16_f32 v1, v2, v3
	global_store_dwordx2 v[36:37], v[16:17], off offset:32
	v_pk_mul_f32 v[16:17], v[28:29], v[32:33] op_sel_hi:[1,0]
	v_pk_mul_f32 v[18:19], v[30:31], v[32:33] op_sel_hi:[1,0]
	global_store_dwordx2 v[36:37], v[0:1], off offset:96
	v_pk_mul_f32 v[0:1], v[12:13], v[32:33] op_sel_hi:[1,0]
	v_pk_mul_f32 v[2:3], v[14:15], v[32:33] op_sel_hi:[1,0]
	v_cvt_pk_bf16_f32 v16, v16, v17
	v_cvt_pk_bf16_f32 v17, v18, v19
	v_cvt_pk_bf16_f32 v0, v0, v1
	v_cvt_pk_bf16_f32 v1, v2, v3
	global_store_dwordx2 v[36:37], v[16:17], off offset:48
	global_store_dwordx2 v[36:37], v[0:1], off offset:112
	s_cbranch_execnz .LBB0_924
	s_branch .LBB0_1267
